# P5 epilogue: output rows stored without the non-temporal hint
# speedup vs baseline: 1.0100x; 1.0100x over previous
; DI u32x2 pk4(float a, float b, float c, float d) { u32x2 r; r.x = pk2(a, b); r.y = pk2(c, d); return r; }
; template <int WI, int WGJ, class GetF, class LdF, class FinF>
; DI void staged_rows_rmw(unsigned char* lds, int tid, GetF get, LdF ld, FinF fin) {
;     ...
;     for (int jt = 0; jt < 2; ++jt) {
;         unsigned char* wrow = lds + (wj * 32 + ln) * RS + (wi * WI * 32 + 4 * h) * 2;
; #pragma unroll
;         for (int it = 0; it < WI; ++it)
; #pragma unroll
;             for (int g = 0; g < 4; ++g) *(u32x2*)(wrow + (it * 32 + 8 * g) * 2) = get(it, jt, g);
;         constexpr int NGRP = 2, GSZ = NIT / NGRP;
;         __syncthreads();
; #pragma unroll 1
;         for (int gq = 0; gq < NGRP; ++gq) {
;             decltype(ld(0, 0)) fetched[GSZ];
; #pragma unroll
;             for (int c = 0; c < GSZ; ++c) {
;                 const int idx = tid + (gq * GSZ + c) * NT, lr = idx / NCH, ch = idx % NCH;
;                 fetched[c] = ld((lr >> 5) * 64 + jt * 32 + (lr & 31), ch * 8);
;             }
; DI void phase5(const Params& p, unsigned char* smem, int tid, bool coop) {
;     ...
;             float rsj[2];
; #pragma unroll
;             for (int jt = 0; jt < 2; ++jt)
;                 rsj[jt] = 1.0f / sqrtf(__hip_atomic_load(ssq + tt * 256 + wj * 64 + jt * 32 + ln, __ATOMIC_RELAXED, __HIP_MEMORY_SCOPE_AGENT) * (1.0f / D) + EPS);
;             staged_rows_rmw<4, 4>(lds, te,
;                 [&](int it, int jt, int g) { const f32x4 gv = *(const f32x4*)(p.post_g + f * 256 + wi * 128 + it * 32 + 8 * g + 4 * h); const float rs = rsj[jt];
;                     return pk4(acc[it][jt][4 * g] * rs * gv[0], acc[it][jt][4 * g + 1] * rs * gv[1], acc[it][jt][4 * g + 2] * rs * gv[2], acc[it][jt][4 * g + 3] * rs * gv[3]); },
;                 [&](int row, int col) { const size_t o = (size_t)(tt * 256 + row) * 1024 + f * 256 + col; X8 r; r.a = __builtin_nontemporal_load((const f32x4*)(p.x + o)); r.b = __builtin_nontemporal_load((const f32x4*)(p.x + o + 4)); return r; },
.LBB0_1084:
	s_or_b64 exec, exec, s[6:7]
	s_lshl_b32 s99, s53, 10
	s_add_u32 s6, s10, s99
	s_addc_u32 s7, s11, 0
	v_pk_mul_f32 v[112:113], v[112:113], v[146:147]
	v_pk_mul_f32 v[114:115], v[114:115], v[148:149]
	v_pk_mul_f32 v[48:49], v[48:49], v[146:147]
	v_pk_mul_f32 v[50:51], v[50:51], v[148:149]
	v_pk_mul_f32 v[116:117], v[116:117], v[150:151]
	v_pk_mul_f32 v[118:119], v[118:119], v[152:153]
	v_pk_mul_f32 v[52:53], v[52:53], v[150:151]
	v_pk_mul_f32 v[54:55], v[54:55], v[152:153]
	v_pk_mul_f32 v[120:121], v[120:121], v[154:155]
	v_pk_mul_f32 v[122:123], v[122:123], v[156:157]
	v_pk_mul_f32 v[56:57], v[56:57], v[154:155]
	v_pk_mul_f32 v[58:59], v[58:59], v[156:157]
	v_pk_mul_f32 v[124:125], v[124:125], v[158:159]
	v_pk_mul_f32 v[126:127], v[126:127], v[160:161]
	v_pk_mul_f32 v[60:61], v[60:61], v[158:159]
	v_pk_mul_f32 v[62:63], v[62:63], v[160:161]
	v_pk_mul_f32 v[96:97], v[96:97], v[162:163]
	v_pk_mul_f32 v[98:99], v[98:99], v[164:165]
	v_pk_mul_f32 v[32:33], v[32:33], v[162:163]
	v_pk_mul_f32 v[34:35], v[34:35], v[164:165]
	v_pk_mul_f32 v[100:101], v[100:101], v[166:167]
	v_pk_mul_f32 v[102:103], v[102:103], v[168:169]
	v_pk_mul_f32 v[36:37], v[36:37], v[166:167]
	v_pk_mul_f32 v[38:39], v[38:39], v[168:169]
	v_pk_mul_f32 v[104:105], v[104:105], v[170:171]
	v_pk_mul_f32 v[106:107], v[106:107], v[172:173]
	v_pk_mul_f32 v[40:41], v[40:41], v[170:171]
	v_pk_mul_f32 v[42:43], v[42:43], v[172:173]
	v_pk_mul_f32 v[108:109], v[108:109], v[174:175]
	v_pk_mul_f32 v[110:111], v[110:111], v[176:177]
	v_pk_mul_f32 v[44:45], v[44:45], v[174:175]
	v_pk_mul_f32 v[46:47], v[46:47], v[176:177]
	v_pk_mul_f32 v[80:81], v[80:81], v[178:179]
	v_pk_mul_f32 v[82:83], v[82:83], v[180:181]
	v_pk_mul_f32 v[16:17], v[16:17], v[178:179]
	v_pk_mul_f32 v[18:19], v[18:19], v[180:181]
	v_pk_mul_f32 v[84:85], v[84:85], v[186:187]
	v_pk_mul_f32 v[86:87], v[86:87], v[188:189]
	v_pk_mul_f32 v[20:21], v[20:21], v[186:187]
	v_pk_mul_f32 v[22:23], v[22:23], v[188:189]
	v_pk_mul_f32 v[88:89], v[88:89], v[190:191]
	v_pk_mul_f32 v[90:91], v[90:91], v[192:193]
	v_pk_mul_f32 v[24:25], v[24:25], v[190:191]
	v_pk_mul_f32 v[26:27], v[26:27], v[192:193]
	v_pk_mul_f32 v[92:93], v[92:93], v[198:199]
	v_pk_mul_f32 v[94:95], v[94:95], v[200:201]
	v_pk_mul_f32 v[28:29], v[28:29], v[198:199]
	v_pk_mul_f32 v[30:31], v[30:31], v[200:201]
	v_pk_mul_f32 v[64:65], v[64:65], v[202:203]
	v_pk_mul_f32 v[66:67], v[66:67], v[204:205]
	v_pk_mul_f32 v[0:1], v[0:1], v[202:203]
	v_pk_mul_f32 v[2:3], v[2:3], v[204:205]
	v_pk_mul_f32 v[68:69], v[68:69], v[206:207]
	v_pk_mul_f32 v[70:71], v[70:71], v[208:209]
	v_pk_mul_f32 v[4:5], v[4:5], v[206:207]
	v_pk_mul_f32 v[6:7], v[6:7], v[208:209]
	v_pk_mul_f32 v[72:73], v[72:73], v[210:211]
	v_pk_mul_f32 v[74:75], v[74:75], v[212:213]
	v_pk_mul_f32 v[8:9], v[8:9], v[210:211]
	v_pk_mul_f32 v[10:11], v[10:11], v[212:213]
	v_pk_mul_f32 v[76:77], v[76:77], v[214:215]
	v_pk_mul_f32 v[78:79], v[78:79], v[216:217]
	v_pk_mul_f32 v[12:13], v[12:13], v[214:215]
	v_pk_mul_f32 v[14:15], v[14:15], v[216:217]
	s_lshl_b32 s99, s30, 2
	s_add_u32 s36, s18, s99
	s_addc_u32 s37, s19, 0
	v_add_u32_e32 v252, v134, v143
	v_lshlrev_b32_e32 v252, 2, v252
	s_barrier
	global_load_dword v144, v252, s[36:37] sc1
	global_load_dword v145, v252, s[36:37] offset:128 sc1
	v_add_u32_e32 v252, 0x1000, v254
	global_load_dwordx4 v[218:221], v252, s[100:101] offset:-4096 nt
	global_load_dwordx4 v[222:225], v252, s[100:101] nt
	v_add_u32_e32 v253, 0x3000, v254
	global_load_dwordx4 v[226:229], v253, s[100:101] offset:-4096 nt
	global_load_dwordx4 v[230:233], v253, s[100:101] nt
	v_add_u32_e32 v252, 0x5000, v254
	global_load_dwordx4 v[234:237], v252, s[100:101] offset:-4096 nt
	global_load_dwordx4 v[238:241], v252, s[100:101] nt
	v_add_u32_e32 v253, 0x7000, v254
	global_load_dwordx4 v[242:245], v253, s[100:101] offset:-4096 nt
	global_load_dwordx4 v[248:251], v253, s[100:101] nt
	v_add_u32_e32 v252, 0x9000, v254
	global_load_dwordx4 v[146:149], v252, s[100:101] offset:-4096 nt
	global_load_dwordx4 v[150:153], v252, s[100:101] nt
	v_add_u32_e32 v253, 0xb000, v254
	global_load_dwordx4 v[154:157], v253, s[100:101] offset:-4096 nt
	global_load_dwordx4 v[158:161], v253, s[100:101] nt
	v_add_u32_e32 v252, 0xd000, v254
	global_load_dwordx4 v[162:165], v252, s[100:101] offset:-4096 nt
	global_load_dwordx4 v[166:169], v252, s[100:101] nt
	v_add_u32_e32 v253, 0xf000, v254
	global_load_dwordx4 v[170:173], v253, s[100:101] offset:-4096 nt
	global_load_dwordx4 v[174:177], v253, s[100:101] nt
	v_add_u32_e32 v252, 0x21000, v254
	global_load_dwordx4 v[178:181], v252, s[100:101] offset:-4096 nt
	global_load_dwordx4 v[186:189], v252, s[100:101] nt
	v_add_u32_e32 v253, 0x23000, v254
	global_load_dwordx4 v[190:193], v253, s[100:101] offset:-4096 nt
	global_load_dwordx4 v[198:201], v253, s[100:101] nt
	v_add_u32_e32 v252, 0x25000, v254
	global_load_dwordx4 v[202:205], v252, s[100:101] offset:-4096 nt
	global_load_dwordx4 v[206:209], v252, s[100:101] nt
	v_add_u32_e32 v253, 0x27000, v254
	global_load_dwordx4 v[210:213], v253, s[100:101] offset:-4096 nt
	global_load_dwordx4 v[214:217], v253, s[100:101] nt
	v_lshrrev_b32_e32 v128, 6, v142
	v_and_b32_e32 v129, 3, v128
	v_lshrrev_b32_e32 v128, 2, v128
	v_lshl_or_b32 v129, v129, 5, v143
	v_mul_u32_u24_e32 v129, 0x210, v129
	v_lshl_add_u32 v129, v128, 8, v129
	v_lshrrev_b32_e32 v128, 2, v142
	v_and_b32_e32 v128, 8, v128
	v_add_u32_e32 v129, v129, v128
	v_add_u32_e32 v143, 0x800, v129
	s_waitcnt vmcnt(24)
; DI u32x2 pk4(float a, float b, float c, float d) { u32x2 r; r.x = pk2(a, b); r.y = pk2(c, d); return r; }
; template <int WI, int WGJ, class GetF, class LdF, class FinF>
; DI void staged_rows_rmw(unsigned char* lds, int tid, GetF get, LdF ld, FinF fin) {
;     ...
;     for (int jt = 0; jt < 2; ++jt) {
;         unsigned char* wrow = lds + (wj * 32 + ln) * RS + (wi * WI * 32 + 4 * h) * 2;
; #pragma unroll
;         for (int it = 0; it < WI; ++it)
; #pragma unroll
;             for (int g = 0; g < 4; ++g) *(u32x2*)(wrow + (it * 32 + 8 * g) * 2) = get(it, jt, g);
;         constexpr int NGRP = 2, GSZ = NIT / NGRP;
;         __syncthreads();
; DI void phase5(const Params& p, unsigned char* smem, int tid, bool coop) {
;     ...
; #pragma unroll
;             for (int jt = 0; jt < 2; ++jt)
;                 rsj[jt] = 1.0f / sqrtf(__hip_atomic_load(ssq + tt * 256 + wj * 64 + jt * 32 + ln, __ATOMIC_RELAXED, __HIP_MEMORY_SCOPE_AGENT) * (1.0f / D) + EPS);
;             staged_rows_rmw<4, 4>(lds, te,
;                 [&](int it, int jt, int g) { const f32x4 gv = *(const f32x4*)(p.post_g + f * 256 + wi * 128 + it * 32 + 8 * g + 4 * h); const float rs = rsj[jt];
;                     return pk4(acc[it][jt][4 * g] * rs * gv[0], acc[it][jt][4 * g + 1] * rs * gv[1], acc[it][jt][4 * g + 2] * rs * gv[2], acc[it][jt][4 * g + 3] * rs * gv[3]); },
	v_fmamk_f32 v144, v144, 0x3a800000, v195
	v_fmamk_f32 v145, v145, 0x3a800000, v195
	v_mul_f32_e32 v182, 0x4f800000, v144
	v_cmp_gt_f32_e32 vcc, s49, v144
	v_mul_f32_e32 v183, 0x4f800000, v145
	v_cmp_gt_f32_e64 s[38:39], s49, v145
	v_cndmask_b32_e32 v144, v144, v182, vcc
	v_sqrt_f32_e32 v182, v144
	v_cndmask_b32_e64 v145, v145, v183, s[38:39]
	v_sqrt_f32_e32 v183, v145
	v_add_u32_e32 v184, -1, v182
	v_fma_f32 v130, -v184, v182, v144
	v_add_u32_e32 v128, -1, v183
	v_add_u32_e32 v197, 1, v182
	v_fma_f32 v132, -v128, v183, v145
	v_cmp_ge_f32_e64 s[36:37], 0, v130
	v_add_u32_e32 v129, 1, v183
	v_fma_f32 v131, -v197, v182, v144
	v_cndmask_b32_e64 v182, v182, v184, s[36:37]
	v_cmp_ge_f32_e64 s[36:37], 0, v132
	v_fma_f32 v133, -v129, v183, v145
	s_nop 0
	v_cndmask_b32_e64 v183, v183, v128, s[36:37]
	v_cmp_lt_f32_e64 s[36:37], 0, v131
	s_nop 1
	v_cndmask_b32_e64 v182, v182, v197, s[36:37]
	v_cmp_lt_f32_e64 s[36:37], 0, v133
	v_mul_f32_e32 v184, 0x37800000, v182
	v_cndmask_b32_e32 v182, v182, v184, vcc
	v_cndmask_b32_e64 v183, v183, v129, s[36:37]
	v_cmp_class_f32_e32 vcc, v144, v196
	v_mul_f32_e32 v197, 0x37800000, v183
	v_cndmask_b32_e64 v183, v183, v197, s[38:39]
	v_cndmask_b32_e32 v182, v182, v144, vcc
	v_div_scale_f32 v184, s[38:39], v182, v182, 1.0
	v_rcp_f32_e32 v197, v184
	v_cmp_class_f32_e32 vcc, v145, v196
	s_nop 1
	v_cndmask_b32_e32 v144, v183, v145, vcc
	v_fma_f32 v183, -v184, v197, 1.0
	v_div_scale_f32 v145, vcc, 1.0, v182, 1.0
	v_fmac_f32_e32 v197, v183, v197
	v_mul_f32_e32 v183, v145, v197
	v_fma_f32 v128, -v184, v183, v145
	v_fmac_f32_e32 v183, v128, v197
	v_fma_f32 v145, -v184, v183, v145
	v_div_fmas_f32 v145, v145, v197, v183
	v_div_fixup_f32 v182, v145, v182, 1.0
	v_div_scale_f32 v128, s[34:35], v144, v144, 1.0
	v_rcp_f32_e32 v130, v128
	v_div_scale_f32 v129, vcc, 1.0, v144, 1.0
	v_fma_f32 v131, -v128, v130, 1.0
	v_fmac_f32_e32 v130, v131, v130
	v_mul_f32_e32 v131, v129, v130
	v_fma_f32 v132, -v128, v131, v129
	v_fmac_f32_e32 v131, v132, v130
	v_fma_f32 v128, -v128, v131, v129
	v_div_fmas_f32 v128, v128, v130, v131
	v_div_fixup_f32 v144, v128, v144, 1.0
	v_pk_mul_f32 v[112:113], v[112:113], v[182:183] op_sel_hi:[1,0]
	v_pk_mul_f32 v[114:115], v[114:115], v[182:183] op_sel_hi:[1,0]
	v_pk_mul_f32 v[116:117], v[116:117], v[182:183] op_sel_hi:[1,0]
	v_pk_mul_f32 v[118:119], v[118:119], v[182:183] op_sel_hi:[1,0]
	v_pk_mul_f32 v[120:121], v[120:121], v[182:183] op_sel_hi:[1,0]
	v_pk_mul_f32 v[122:123], v[122:123], v[182:183] op_sel_hi:[1,0]
	v_pk_mul_f32 v[124:125], v[124:125], v[182:183] op_sel_hi:[1,0]
	v_pk_mul_f32 v[126:127], v[126:127], v[182:183] op_sel_hi:[1,0]
	v_pk_mul_f32 v[96:97], v[96:97], v[182:183] op_sel_hi:[1,0]
	v_pk_mul_f32 v[98:99], v[98:99], v[182:183] op_sel_hi:[1,0]
	v_pk_mul_f32 v[100:101], v[100:101], v[182:183] op_sel_hi:[1,0]
	v_pk_mul_f32 v[102:103], v[102:103], v[182:183] op_sel_hi:[1,0]
	v_pk_mul_f32 v[104:105], v[104:105], v[182:183] op_sel_hi:[1,0]
	v_pk_mul_f32 v[106:107], v[106:107], v[182:183] op_sel_hi:[1,0]
	v_pk_mul_f32 v[108:109], v[108:109], v[182:183] op_sel_hi:[1,0]
	v_pk_mul_f32 v[110:111], v[110:111], v[182:183] op_sel_hi:[1,0]
	v_pk_mul_f32 v[80:81], v[80:81], v[182:183] op_sel_hi:[1,0]
	v_pk_mul_f32 v[82:83], v[82:83], v[182:183] op_sel_hi:[1,0]
	v_pk_mul_f32 v[84:85], v[84:85], v[182:183] op_sel_hi:[1,0]
	v_pk_mul_f32 v[86:87], v[86:87], v[182:183] op_sel_hi:[1,0]
	v_pk_mul_f32 v[88:89], v[88:89], v[182:183] op_sel_hi:[1,0]
	v_pk_mul_f32 v[90:91], v[90:91], v[182:183] op_sel_hi:[1,0]
	v_pk_mul_f32 v[92:93], v[92:93], v[182:183] op_sel_hi:[1,0]
	v_pk_mul_f32 v[94:95], v[94:95], v[182:183] op_sel_hi:[1,0]
	v_pk_mul_f32 v[64:65], v[64:65], v[182:183] op_sel_hi:[1,0]
	v_pk_mul_f32 v[66:67], v[66:67], v[182:183] op_sel_hi:[1,0]
	v_pk_mul_f32 v[68:69], v[68:69], v[182:183] op_sel_hi:[1,0]
	v_pk_mul_f32 v[70:71], v[70:71], v[182:183] op_sel_hi:[1,0]
	v_pk_mul_f32 v[72:73], v[72:73], v[182:183] op_sel_hi:[1,0]
	v_pk_mul_f32 v[74:75], v[74:75], v[182:183] op_sel_hi:[1,0]
	v_pk_mul_f32 v[76:77], v[76:77], v[182:183] op_sel_hi:[1,0]
	v_pk_mul_f32 v[78:79], v[78:79], v[182:183] op_sel_hi:[1,0]
	v_cvt_pk_bf16_f32 v112, v112, v113
	v_cvt_pk_bf16_f32 v113, v114, v115
	v_cvt_pk_bf16_f32 v116, v116, v117
	v_cvt_pk_bf16_f32 v117, v118, v119
	v_cvt_pk_bf16_f32 v120, v120, v121
	v_cvt_pk_bf16_f32 v121, v122, v123
	v_cvt_pk_bf16_f32 v124, v124, v125
	v_cvt_pk_bf16_f32 v125, v126, v127
	v_cvt_pk_bf16_f32 v96, v96, v97
	v_cvt_pk_bf16_f32 v97, v98, v99
	v_cvt_pk_bf16_f32 v100, v100, v101
	v_cvt_pk_bf16_f32 v101, v102, v103
	v_cvt_pk_bf16_f32 v104, v104, v105
	v_cvt_pk_bf16_f32 v105, v106, v107
	v_cvt_pk_bf16_f32 v108, v108, v109
	v_cvt_pk_bf16_f32 v109, v110, v111
	v_cvt_pk_bf16_f32 v80, v80, v81
	v_cvt_pk_bf16_f32 v81, v82, v83
	v_cvt_pk_bf16_f32 v84, v84, v85
	v_cvt_pk_bf16_f32 v85, v86, v87
	v_cvt_pk_bf16_f32 v88, v88, v89
	v_cvt_pk_bf16_f32 v89, v90, v91
	v_cvt_pk_bf16_f32 v92, v92, v93
	v_cvt_pk_bf16_f32 v93, v94, v95
	v_cvt_pk_bf16_f32 v64, v64, v65
	v_cvt_pk_bf16_f32 v65, v66, v67
	v_cvt_pk_bf16_f32 v68, v68, v69
	v_cvt_pk_bf16_f32 v69, v70, v71
	v_cvt_pk_bf16_f32 v72, v72, v73
	v_cvt_pk_bf16_f32 v73, v74, v75
	v_cvt_pk_bf16_f32 v76, v76, v77
	v_cvt_pk_bf16_f32 v77, v78, v79
	ds_write2_b64 v143, v[112:113], v[116:117] offset0:0 offset1:2
	ds_write2_b64 v143, v[120:121], v[124:125] offset0:4 offset1:6
	ds_write2_b64 v143, v[96:97], v[100:101] offset0:8 offset1:10
	ds_write2_b64 v143, v[104:105], v[108:109] offset0:12 offset1:14
	ds_write2_b64 v143, v[80:81], v[84:85] offset0:16 offset1:18
	ds_write2_b64 v143, v[88:89], v[92:93] offset0:20 offset1:22
	ds_write2_b64 v143, v[64:65], v[68:69] offset0:24 offset1:26
	ds_write2_b64 v143, v[72:73], v[76:77] offset0:28 offset1:30
	s_waitcnt lgkmcnt(0)
	s_barrier
; DI float bf_lo(unsigned u) { return __uint_as_float(u << 16); }
; DI float bf_hi(unsigned u) { return __uint_as_float(u & 0xffff0000u); }
; template <int WI, int WGJ, class GetF, class LdF, class FinF>
; DI void staged_rows_rmw(unsigned char* lds, int tid, GetF get, LdF ld, FinF fin) {
;     ...
;     for (int jt = 0; jt < 2; ++jt) {
;         unsigned char* wrow = lds + (wj * 32 + ln) * RS + (wi * WI * 32 + 4 * h) * 2;
; #pragma unroll
;         for (int it = 0; it < WI; ++it)
; #pragma unroll
;             for (int g = 0; g < 4; ++g) *(u32x2*)(wrow + (it * 32 + 8 * g) * 2) = get(it, jt, g);
;         constexpr int NGRP = 2, GSZ = NIT / NGRP;
;         __syncthreads();
; #pragma unroll 1
;         for (int gq = 0; gq < NGRP; ++gq) {
;             decltype(ld(0, 0)) fetched[GSZ];
; #pragma unroll
;             for (int c = 0; c < GSZ; ++c) {
;                 const int idx = tid + (gq * GSZ + c) * NT, lr = idx / NCH, ch = idx % NCH;
;                 fetched[c] = ld((lr >> 5) * 64 + jt * 32 + (lr & 31), ch * 8);
;             }
; #pragma unroll
;             for (int c = 0; c < GSZ; ++c) {
;                 const int idx = tid + (gq * GSZ + c) * NT, lr = idx / NCH, ch = idx % NCH;
;                 const u32x4 v = *(const u32x4*)(lds + lr * RS + ch * 16);
;                 fin((lr >> 5) * 64 + jt * 32 + (lr & 31), ch * 8, v, fetched[c]);
;             }
; DI void phase5(const Params& p, unsigned char* smem, int tid, bool coop) {
;     ...
;                 [&](int row, int col, u32x4 v, X8 xv) { const size_t o = (size_t)(tt * 256 + row) * 1024 + f * 256 + col;
;                     __builtin_nontemporal_store((f32x4){xv.a[0] + bf_lo(v[0]), xv.a[1] + bf_hi(v[0]), xv.a[2] + bf_lo(v[1]), xv.a[3] + bf_hi(v[1])}, (f32x4*)(p.out + o));
;                     __builtin_nontemporal_store((f32x4){xv.b[0] + bf_lo(v[2]), xv.b[1] + bf_hi(v[2]), xv.b[2] + bf_lo(v[3]), xv.b[3] + bf_hi(v[3])}, (f32x4*)(p.out + o + 4)); });
	ds_read_b64 v[64:65], v246 offset:2048
	ds_read_b64 v[66:67], v246 offset:2576
	ds_read_b64 v[68:69], v246 offset:3104
	ds_read_b64 v[70:71], v246 offset:3632
	ds_read_b64 v[72:73], v246 offset:4160
	ds_read_b64 v[74:75], v246 offset:4688
	ds_read_b64 v[76:77], v246 offset:5216
	ds_read_b64 v[78:79], v246 offset:5744
	ds_read_b64 v[80:81], v246 offset:6272
	ds_read_b64 v[82:83], v246 offset:6800
	ds_read_b64 v[84:85], v246 offset:7328
	ds_read_b64 v[86:87], v246 offset:7856
	ds_read_b64 v[88:89], v246 offset:8384
	ds_read_b64 v[90:91], v246 offset:8912
	ds_read_b64 v[92:93], v246 offset:9440
	ds_read_b64 v[94:95], v246 offset:9968
	v_pk_mul_f32 v[48:49], v[48:49], v[144:145] op_sel_hi:[1,0]
	v_pk_mul_f32 v[50:51], v[50:51], v[144:145] op_sel_hi:[1,0]
	v_pk_mul_f32 v[52:53], v[52:53], v[144:145] op_sel_hi:[1,0]
	v_pk_mul_f32 v[54:55], v[54:55], v[144:145] op_sel_hi:[1,0]
	v_pk_mul_f32 v[56:57], v[56:57], v[144:145] op_sel_hi:[1,0]
	v_pk_mul_f32 v[58:59], v[58:59], v[144:145] op_sel_hi:[1,0]
	v_pk_mul_f32 v[60:61], v[60:61], v[144:145] op_sel_hi:[1,0]
	v_pk_mul_f32 v[62:63], v[62:63], v[144:145] op_sel_hi:[1,0]
	v_pk_mul_f32 v[32:33], v[32:33], v[144:145] op_sel_hi:[1,0]
	v_pk_mul_f32 v[34:35], v[34:35], v[144:145] op_sel_hi:[1,0]
	v_pk_mul_f32 v[36:37], v[36:37], v[144:145] op_sel_hi:[1,0]
	v_pk_mul_f32 v[38:39], v[38:39], v[144:145] op_sel_hi:[1,0]
	v_pk_mul_f32 v[40:41], v[40:41], v[144:145] op_sel_hi:[1,0]
	v_pk_mul_f32 v[42:43], v[42:43], v[144:145] op_sel_hi:[1,0]
	v_pk_mul_f32 v[44:45], v[44:45], v[144:145] op_sel_hi:[1,0]
	v_pk_mul_f32 v[46:47], v[46:47], v[144:145] op_sel_hi:[1,0]
	v_pk_mul_f32 v[16:17], v[16:17], v[144:145] op_sel_hi:[1,0]
	v_pk_mul_f32 v[18:19], v[18:19], v[144:145] op_sel_hi:[1,0]
	v_pk_mul_f32 v[20:21], v[20:21], v[144:145] op_sel_hi:[1,0]
	v_pk_mul_f32 v[22:23], v[22:23], v[144:145] op_sel_hi:[1,0]
	v_pk_mul_f32 v[24:25], v[24:25], v[144:145] op_sel_hi:[1,0]
	v_pk_mul_f32 v[26:27], v[26:27], v[144:145] op_sel_hi:[1,0]
	v_pk_mul_f32 v[28:29], v[28:29], v[144:145] op_sel_hi:[1,0]
	v_pk_mul_f32 v[30:31], v[30:31], v[144:145] op_sel_hi:[1,0]
	v_pk_mul_f32 v[0:1], v[0:1], v[144:145] op_sel_hi:[1,0]
	v_pk_mul_f32 v[2:3], v[2:3], v[144:145] op_sel_hi:[1,0]
	v_pk_mul_f32 v[4:5], v[4:5], v[144:145] op_sel_hi:[1,0]
	v_pk_mul_f32 v[6:7], v[6:7], v[144:145] op_sel_hi:[1,0]
	v_pk_mul_f32 v[8:9], v[8:9], v[144:145] op_sel_hi:[1,0]
	v_pk_mul_f32 v[10:11], v[10:11], v[144:145] op_sel_hi:[1,0]
	v_pk_mul_f32 v[12:13], v[12:13], v[144:145] op_sel_hi:[1,0]
	v_pk_mul_f32 v[14:15], v[14:15], v[144:145] op_sel_hi:[1,0]
	v_cvt_pk_bf16_f32 v48, v48, v49
	v_cvt_pk_bf16_f32 v49, v50, v51
	v_cvt_pk_bf16_f32 v52, v52, v53
	v_cvt_pk_bf16_f32 v53, v54, v55
	v_cvt_pk_bf16_f32 v56, v56, v57
	v_cvt_pk_bf16_f32 v57, v58, v59
	v_cvt_pk_bf16_f32 v60, v60, v61
	v_cvt_pk_bf16_f32 v61, v62, v63
	v_cvt_pk_bf16_f32 v32, v32, v33
	v_cvt_pk_bf16_f32 v33, v34, v35
	v_cvt_pk_bf16_f32 v36, v36, v37
	v_cvt_pk_bf16_f32 v37, v38, v39
	v_cvt_pk_bf16_f32 v40, v40, v41
	v_cvt_pk_bf16_f32 v41, v42, v43
	v_cvt_pk_bf16_f32 v44, v44, v45
	v_cvt_pk_bf16_f32 v45, v46, v47
	v_cvt_pk_bf16_f32 v16, v16, v17
	v_cvt_pk_bf16_f32 v17, v18, v19
	v_cvt_pk_bf16_f32 v20, v20, v21
	v_cvt_pk_bf16_f32 v21, v22, v23
	v_cvt_pk_bf16_f32 v24, v24, v25
	v_cvt_pk_bf16_f32 v25, v26, v27
	v_cvt_pk_bf16_f32 v28, v28, v29
	v_cvt_pk_bf16_f32 v29, v30, v31
	v_cvt_pk_bf16_f32 v0, v0, v1
	v_cvt_pk_bf16_f32 v1, v2, v3
	v_cvt_pk_bf16_f32 v4, v4, v5
	v_cvt_pk_bf16_f32 v5, v6, v7
	v_cvt_pk_bf16_f32 v8, v8, v9
	v_cvt_pk_bf16_f32 v9, v10, v11
	v_cvt_pk_bf16_f32 v12, v12, v13
	v_cvt_pk_bf16_f32 v13, v14, v15
	s_waitcnt lgkmcnt(0)
	s_barrier
	ds_write2_b64 v143, v[48:49], v[52:53] offset0:0 offset1:2
	ds_write2_b64 v143, v[56:57], v[60:61] offset0:4 offset1:6
	ds_write2_b64 v143, v[32:33], v[36:37] offset0:8 offset1:10
	ds_write2_b64 v143, v[40:41], v[44:45] offset0:12 offset1:14
	ds_write2_b64 v143, v[16:17], v[20:21] offset0:16 offset1:18
	ds_write2_b64 v143, v[24:25], v[28:29] offset0:20 offset1:22
	ds_write2_b64 v143, v[0:1], v[4:5] offset0:24 offset1:26
	ds_write2_b64 v143, v[8:9], v[12:13] offset0:28 offset1:30
	s_waitcnt lgkmcnt(0)
	s_barrier
	ds_read_b64 v[0:1], v246 offset:2048
	ds_read_b64 v[2:3], v246 offset:2576
	ds_read_b64 v[4:5], v246 offset:3104
	ds_read_b64 v[6:7], v246 offset:3632
	ds_read_b64 v[8:9], v246 offset:4160
	ds_read_b64 v[10:11], v246 offset:4688
	ds_read_b64 v[12:13], v246 offset:5216
	ds_read_b64 v[14:15], v246 offset:5744
	ds_read_b64 v[16:17], v246 offset:6272
	ds_read_b64 v[18:19], v246 offset:6800
	ds_read_b64 v[20:21], v246 offset:7328
	ds_read_b64 v[22:23], v246 offset:7856
	ds_read_b64 v[24:25], v246 offset:8384
	ds_read_b64 v[26:27], v246 offset:8912
	ds_read_b64 v[28:29], v246 offset:9440
	ds_read_b64 v[30:31], v246 offset:9968
	v_lshlrev_b32_e32 v96, 16, v64
	v_and_b32_e32 v97, 0xffff0000, v64
	v_lshlrev_b32_e32 v98, 16, v65
	v_and_b32_e32 v99, 0xffff0000, v65
	s_waitcnt vmcnt(23)
	v_pk_add_f32 v[218:219], v[218:219], v[96:97]
	v_pk_add_f32 v[220:221], v[220:221], v[98:99]
	v_add_u32_e32 v252, 0x1000, v254
	global_store_dwordx4 v252, v[218:221], s[6:7] offset:-4096
	v_lshlrev_b32_e32 v100, 16, v66
	v_and_b32_e32 v101, 0xffff0000, v66
	v_lshlrev_b32_e32 v102, 16, v67
	v_and_b32_e32 v103, 0xffff0000, v67
	s_waitcnt vmcnt(23)
	v_pk_add_f32 v[222:223], v[222:223], v[100:101]
	v_pk_add_f32 v[224:225], v[224:225], v[102:103]
	global_store_dwordx4 v252, v[222:225], s[6:7]
	v_lshlrev_b32_e32 v96, 16, v68
	v_and_b32_e32 v97, 0xffff0000, v68
	v_lshlrev_b32_e32 v98, 16, v69
	v_and_b32_e32 v99, 0xffff0000, v69
	s_waitcnt vmcnt(23)
; DI float bf_lo(unsigned u) { return __uint_as_float(u << 16); }
; DI float bf_hi(unsigned u) { return __uint_as_float(u & 0xffff0000u); }
; template <int WI, int WGJ, class GetF, class LdF, class FinF>
; DI void staged_rows_rmw(unsigned char* lds, int tid, GetF get, LdF ld, FinF fin) {
;     ...
;         for (int gq = 0; gq < NGRP; ++gq) {
;             decltype(ld(0, 0)) fetched[GSZ];
; #pragma unroll
;             for (int c = 0; c < GSZ; ++c) {
;                 const int idx = tid + (gq * GSZ + c) * NT, lr = idx / NCH, ch = idx % NCH;
;                 fetched[c] = ld((lr >> 5) * 64 + jt * 32 + (lr & 31), ch * 8);
;             }
; #pragma unroll
;             for (int c = 0; c < GSZ; ++c) {
;                 const int idx = tid + (gq * GSZ + c) * NT, lr = idx / NCH, ch = idx % NCH;
;                 const u32x4 v = *(const u32x4*)(lds + lr * RS + ch * 16);
;                 fin((lr >> 5) * 64 + jt * 32 + (lr & 31), ch * 8, v, fetched[c]);
;             }
; DI void phase5(const Params& p, unsigned char* smem, int tid, bool coop) {
;     ...
;                 [&](int row, int col, u32x4 v, X8 xv) { const size_t o = (size_t)(tt * 256 + row) * 1024 + f * 256 + col;
;                     __builtin_nontemporal_store((f32x4){xv.a[0] + bf_lo(v[0]), xv.a[1] + bf_hi(v[0]), xv.a[2] + bf_lo(v[1]), xv.a[3] + bf_hi(v[1])}, (f32x4*)(p.out + o));
;                     __builtin_nontemporal_store((f32x4){xv.b[0] + bf_lo(v[2]), xv.b[1] + bf_hi(v[2]), xv.b[2] + bf_lo(v[3]), xv.b[3] + bf_hi(v[3])}, (f32x4*)(p.out + o + 4)); });
	v_pk_add_f32 v[226:227], v[226:227], v[96:97]
	v_pk_add_f32 v[228:229], v[228:229], v[98:99]
	v_add_u32_e32 v253, 0x3000, v254
	global_store_dwordx4 v253, v[226:229], s[6:7] offset:-4096
	v_lshlrev_b32_e32 v100, 16, v70
	v_and_b32_e32 v101, 0xffff0000, v70
	v_lshlrev_b32_e32 v102, 16, v71
	v_and_b32_e32 v103, 0xffff0000, v71
	s_waitcnt vmcnt(23)
	v_pk_add_f32 v[230:231], v[230:231], v[100:101]
	v_pk_add_f32 v[232:233], v[232:233], v[102:103]
	global_store_dwordx4 v253, v[230:233], s[6:7]
	v_lshlrev_b32_e32 v96, 16, v72
	v_and_b32_e32 v97, 0xffff0000, v72
	v_lshlrev_b32_e32 v98, 16, v73
	v_and_b32_e32 v99, 0xffff0000, v73
	s_waitcnt vmcnt(23)
	v_pk_add_f32 v[234:235], v[234:235], v[96:97]
	v_pk_add_f32 v[236:237], v[236:237], v[98:99]
	v_add_u32_e32 v252, 0x5000, v254
	global_store_dwordx4 v252, v[234:237], s[6:7] offset:-4096
	v_lshlrev_b32_e32 v100, 16, v74
	v_and_b32_e32 v101, 0xffff0000, v74
	v_lshlrev_b32_e32 v102, 16, v75
	v_and_b32_e32 v103, 0xffff0000, v75
	s_waitcnt vmcnt(23)
	v_pk_add_f32 v[238:239], v[238:239], v[100:101]
	v_pk_add_f32 v[240:241], v[240:241], v[102:103]
	global_store_dwordx4 v252, v[238:241], s[6:7]
	v_lshlrev_b32_e32 v96, 16, v76
	v_and_b32_e32 v97, 0xffff0000, v76
	v_lshlrev_b32_e32 v98, 16, v77
	v_and_b32_e32 v99, 0xffff0000, v77
	s_waitcnt vmcnt(23)
	v_pk_add_f32 v[242:243], v[242:243], v[96:97]
	v_pk_add_f32 v[244:245], v[244:245], v[98:99]
	v_add_u32_e32 v253, 0x7000, v254
	global_store_dwordx4 v253, v[242:245], s[6:7] offset:-4096
	v_lshlrev_b32_e32 v100, 16, v78
	v_and_b32_e32 v101, 0xffff0000, v78
	v_lshlrev_b32_e32 v102, 16, v79
	v_and_b32_e32 v103, 0xffff0000, v79
	s_waitcnt vmcnt(23)
	v_pk_add_f32 v[248:249], v[248:249], v[100:101]
	v_pk_add_f32 v[250:251], v[250:251], v[102:103]
	global_store_dwordx4 v253, v[248:251], s[6:7]
	v_add_u32_e32 v252, 0x29000, v254
	global_load_dwordx4 v[218:221], v252, s[100:101] offset:-4096 nt
	global_load_dwordx4 v[222:225], v252, s[100:101] nt
	v_add_u32_e32 v253, 0x2b000, v254
	global_load_dwordx4 v[226:229], v253, s[100:101] offset:-4096 nt
	global_load_dwordx4 v[230:233], v253, s[100:101] nt
	v_add_u32_e32 v252, 0x2d000, v254
	global_load_dwordx4 v[234:237], v252, s[100:101] offset:-4096 nt
	global_load_dwordx4 v[238:241], v252, s[100:101] nt
	v_add_u32_e32 v253, 0x2f000, v254
	global_load_dwordx4 v[242:245], v253, s[100:101] offset:-4096 nt
	global_load_dwordx4 v[248:251], v253, s[100:101] nt
	v_lshlrev_b32_e32 v96, 16, v80
	v_and_b32_e32 v97, 0xffff0000, v80
	v_lshlrev_b32_e32 v98, 16, v81
	v_and_b32_e32 v99, 0xffff0000, v81
	s_waitcnt vmcnt(31)
	v_pk_add_f32 v[146:147], v[146:147], v[96:97]
	v_pk_add_f32 v[148:149], v[148:149], v[98:99]
	v_add_u32_e32 v252, 0x9000, v254
	global_store_dwordx4 v252, v[146:149], s[6:7] offset:-4096
	v_lshlrev_b32_e32 v100, 16, v82
	v_and_b32_e32 v101, 0xffff0000, v82
	v_lshlrev_b32_e32 v102, 16, v83
	v_and_b32_e32 v103, 0xffff0000, v83
	s_waitcnt vmcnt(31)
	v_pk_add_f32 v[150:151], v[150:151], v[100:101]
	v_pk_add_f32 v[152:153], v[152:153], v[102:103]
	global_store_dwordx4 v252, v[150:153], s[6:7]
	v_lshlrev_b32_e32 v96, 16, v84
	v_and_b32_e32 v97, 0xffff0000, v84
	v_lshlrev_b32_e32 v98, 16, v85
	v_and_b32_e32 v99, 0xffff0000, v85
	s_waitcnt vmcnt(31)
	v_pk_add_f32 v[154:155], v[154:155], v[96:97]
	v_pk_add_f32 v[156:157], v[156:157], v[98:99]
	v_add_u32_e32 v253, 0xb000, v254
	global_store_dwordx4 v253, v[154:157], s[6:7] offset:-4096
	v_lshlrev_b32_e32 v100, 16, v86
	v_and_b32_e32 v101, 0xffff0000, v86
	v_lshlrev_b32_e32 v102, 16, v87
	v_and_b32_e32 v103, 0xffff0000, v87
	s_waitcnt vmcnt(31)
	v_pk_add_f32 v[158:159], v[158:159], v[100:101]
	v_pk_add_f32 v[160:161], v[160:161], v[102:103]
	global_store_dwordx4 v253, v[158:161], s[6:7]
	v_lshlrev_b32_e32 v96, 16, v88
	v_and_b32_e32 v97, 0xffff0000, v88
	v_lshlrev_b32_e32 v98, 16, v89
	v_and_b32_e32 v99, 0xffff0000, v89
	s_waitcnt vmcnt(31)
	v_pk_add_f32 v[162:163], v[162:163], v[96:97]
	v_pk_add_f32 v[164:165], v[164:165], v[98:99]
	v_add_u32_e32 v252, 0xd000, v254
	global_store_dwordx4 v252, v[162:165], s[6:7] offset:-4096
	v_lshlrev_b32_e32 v100, 16, v90
	v_and_b32_e32 v101, 0xffff0000, v90
	v_lshlrev_b32_e32 v102, 16, v91
	v_and_b32_e32 v103, 0xffff0000, v91
	s_waitcnt vmcnt(31)
	v_pk_add_f32 v[166:167], v[166:167], v[100:101]
	v_pk_add_f32 v[168:169], v[168:169], v[102:103]
	global_store_dwordx4 v252, v[166:169], s[6:7]
	v_lshlrev_b32_e32 v96, 16, v92
	v_and_b32_e32 v97, 0xffff0000, v92
	v_lshlrev_b32_e32 v98, 16, v93
	v_and_b32_e32 v99, 0xffff0000, v93
	s_waitcnt vmcnt(31)
	v_pk_add_f32 v[170:171], v[170:171], v[96:97]
	v_pk_add_f32 v[172:173], v[172:173], v[98:99]
	v_add_u32_e32 v253, 0xf000, v254
	global_store_dwordx4 v253, v[170:173], s[6:7] offset:-4096
	v_lshlrev_b32_e32 v100, 16, v94
	v_and_b32_e32 v101, 0xffff0000, v94
	v_lshlrev_b32_e32 v102, 16, v95
	v_and_b32_e32 v103, 0xffff0000, v95
	s_waitcnt vmcnt(31)
	v_pk_add_f32 v[174:175], v[174:175], v[100:101]
	v_pk_add_f32 v[176:177], v[176:177], v[102:103]
	global_store_dwordx4 v253, v[174:177], s[6:7]
	s_waitcnt lgkmcnt(0)
	v_lshlrev_b32_e32 v96, 16, v0
	v_and_b32_e32 v97, 0xffff0000, v0
	v_lshlrev_b32_e32 v98, 16, v1
	v_and_b32_e32 v99, 0xffff0000, v1
	s_waitcnt vmcnt(31)
; DI float bf_lo(unsigned u) { return __uint_as_float(u << 16); }
; DI float bf_hi(unsigned u) { return __uint_as_float(u & 0xffff0000u); }
; template <int WI, int WGJ, class GetF, class LdF, class FinF>
; DI void staged_rows_rmw(unsigned char* lds, int tid, GetF get, LdF ld, FinF fin) {
;     ...
;         for (int gq = 0; gq < NGRP; ++gq) {
;             decltype(ld(0, 0)) fetched[GSZ];
; #pragma unroll
;             for (int c = 0; c < GSZ; ++c) {
;                 const int idx = tid + (gq * GSZ + c) * NT, lr = idx / NCH, ch = idx % NCH;
;                 fetched[c] = ld((lr >> 5) * 64 + jt * 32 + (lr & 31), ch * 8);
;             }
; #pragma unroll
;             for (int c = 0; c < GSZ; ++c) {
;                 const int idx = tid + (gq * GSZ + c) * NT, lr = idx / NCH, ch = idx % NCH;
;                 const u32x4 v = *(const u32x4*)(lds + lr * RS + ch * 16);
;                 fin((lr >> 5) * 64 + jt * 32 + (lr & 31), ch * 8, v, fetched[c]);
;             }
;         }
;         __syncthreads();
; DI void phase5(const Params& p, unsigned char* smem, int tid, bool coop) {
;     ...
;                 [&](int row, int col, u32x4 v, X8 xv) { const size_t o = (size_t)(tt * 256 + row) * 1024 + f * 256 + col;
;                     __builtin_nontemporal_store((f32x4){xv.a[0] + bf_lo(v[0]), xv.a[1] + bf_hi(v[0]), xv.a[2] + bf_lo(v[1]), xv.a[3] + bf_hi(v[1])}, (f32x4*)(p.out + o));
;                     __builtin_nontemporal_store((f32x4){xv.b[0] + bf_lo(v[2]), xv.b[1] + bf_hi(v[2]), xv.b[2] + bf_lo(v[3]), xv.b[3] + bf_hi(v[3])}, (f32x4*)(p.out + o + 4)); });
	v_pk_add_f32 v[178:179], v[178:179], v[96:97]
	v_pk_add_f32 v[180:181], v[180:181], v[98:99]
	v_add_u32_e32 v252, 0x21000, v254
	global_store_dwordx4 v252, v[178:181], s[6:7] offset:-4096
	v_lshlrev_b32_e32 v100, 16, v2
	v_and_b32_e32 v101, 0xffff0000, v2
	v_lshlrev_b32_e32 v102, 16, v3
	v_and_b32_e32 v103, 0xffff0000, v3
	s_waitcnt vmcnt(31)
	v_pk_add_f32 v[186:187], v[186:187], v[100:101]
	v_pk_add_f32 v[188:189], v[188:189], v[102:103]
	global_store_dwordx4 v252, v[186:189], s[6:7]
	v_lshlrev_b32_e32 v96, 16, v4
	v_and_b32_e32 v97, 0xffff0000, v4
	v_lshlrev_b32_e32 v98, 16, v5
	v_and_b32_e32 v99, 0xffff0000, v5
	s_waitcnt vmcnt(31)
	v_pk_add_f32 v[190:191], v[190:191], v[96:97]
	v_pk_add_f32 v[192:193], v[192:193], v[98:99]
	v_add_u32_e32 v253, 0x23000, v254
	global_store_dwordx4 v253, v[190:193], s[6:7] offset:-4096
	v_lshlrev_b32_e32 v100, 16, v6
	v_and_b32_e32 v101, 0xffff0000, v6
	v_lshlrev_b32_e32 v102, 16, v7
	v_and_b32_e32 v103, 0xffff0000, v7
	s_waitcnt vmcnt(31)
	v_pk_add_f32 v[198:199], v[198:199], v[100:101]
	v_pk_add_f32 v[200:201], v[200:201], v[102:103]
	global_store_dwordx4 v253, v[198:201], s[6:7]
	v_lshlrev_b32_e32 v96, 16, v8
	v_and_b32_e32 v97, 0xffff0000, v8
	v_lshlrev_b32_e32 v98, 16, v9
	v_and_b32_e32 v99, 0xffff0000, v9
	s_waitcnt vmcnt(31)
	v_pk_add_f32 v[202:203], v[202:203], v[96:97]
	v_pk_add_f32 v[204:205], v[204:205], v[98:99]
	v_add_u32_e32 v252, 0x25000, v254
	global_store_dwordx4 v252, v[202:205], s[6:7] offset:-4096
	v_lshlrev_b32_e32 v100, 16, v10
	v_and_b32_e32 v101, 0xffff0000, v10
	v_lshlrev_b32_e32 v102, 16, v11
	v_and_b32_e32 v103, 0xffff0000, v11
	s_waitcnt vmcnt(31)
	v_pk_add_f32 v[206:207], v[206:207], v[100:101]
	v_pk_add_f32 v[208:209], v[208:209], v[102:103]
	global_store_dwordx4 v252, v[206:209], s[6:7]
	v_lshlrev_b32_e32 v96, 16, v12
	v_and_b32_e32 v97, 0xffff0000, v12
	v_lshlrev_b32_e32 v98, 16, v13
	v_and_b32_e32 v99, 0xffff0000, v13
	s_waitcnt vmcnt(31)
	v_pk_add_f32 v[210:211], v[210:211], v[96:97]
	v_pk_add_f32 v[212:213], v[212:213], v[98:99]
	v_add_u32_e32 v253, 0x27000, v254
	global_store_dwordx4 v253, v[210:213], s[6:7] offset:-4096
	v_lshlrev_b32_e32 v100, 16, v14
	v_and_b32_e32 v101, 0xffff0000, v14
	v_lshlrev_b32_e32 v102, 16, v15
	v_and_b32_e32 v103, 0xffff0000, v15
	s_waitcnt vmcnt(31)
	v_pk_add_f32 v[214:215], v[214:215], v[100:101]
	v_pk_add_f32 v[216:217], v[216:217], v[102:103]
	global_store_dwordx4 v253, v[214:217], s[6:7]
	v_lshlrev_b32_e32 v96, 16, v16
	v_and_b32_e32 v97, 0xffff0000, v16
	v_lshlrev_b32_e32 v98, 16, v17
	v_and_b32_e32 v99, 0xffff0000, v17
	s_waitcnt vmcnt(23)
	v_pk_add_f32 v[218:219], v[218:219], v[96:97]
	v_pk_add_f32 v[220:221], v[220:221], v[98:99]
	v_add_u32_e32 v252, 0x29000, v254
	global_store_dwordx4 v252, v[218:221], s[6:7] offset:-4096
	v_lshlrev_b32_e32 v100, 16, v18
	v_and_b32_e32 v101, 0xffff0000, v18
	v_lshlrev_b32_e32 v102, 16, v19
	v_and_b32_e32 v103, 0xffff0000, v19
	s_waitcnt vmcnt(23)
	v_pk_add_f32 v[222:223], v[222:223], v[100:101]
	v_pk_add_f32 v[224:225], v[224:225], v[102:103]
	global_store_dwordx4 v252, v[222:225], s[6:7]
	v_lshlrev_b32_e32 v96, 16, v20
	v_and_b32_e32 v97, 0xffff0000, v20
	v_lshlrev_b32_e32 v98, 16, v21
	v_and_b32_e32 v99, 0xffff0000, v21
	s_waitcnt vmcnt(23)
	v_pk_add_f32 v[226:227], v[226:227], v[96:97]
	v_pk_add_f32 v[228:229], v[228:229], v[98:99]
	v_add_u32_e32 v253, 0x2b000, v254
	global_store_dwordx4 v253, v[226:229], s[6:7] offset:-4096
	v_lshlrev_b32_e32 v100, 16, v22
	v_and_b32_e32 v101, 0xffff0000, v22
	v_lshlrev_b32_e32 v102, 16, v23
	v_and_b32_e32 v103, 0xffff0000, v23
	s_waitcnt vmcnt(23)
	v_pk_add_f32 v[230:231], v[230:231], v[100:101]
	v_pk_add_f32 v[232:233], v[232:233], v[102:103]
	global_store_dwordx4 v253, v[230:233], s[6:7]
	v_lshlrev_b32_e32 v96, 16, v24
	v_and_b32_e32 v97, 0xffff0000, v24
	v_lshlrev_b32_e32 v98, 16, v25
	v_and_b32_e32 v99, 0xffff0000, v25
	s_waitcnt vmcnt(23)
	v_pk_add_f32 v[234:235], v[234:235], v[96:97]
	v_pk_add_f32 v[236:237], v[236:237], v[98:99]
	v_add_u32_e32 v252, 0x2d000, v254
	global_store_dwordx4 v252, v[234:237], s[6:7] offset:-4096
	v_lshlrev_b32_e32 v100, 16, v26
	v_and_b32_e32 v101, 0xffff0000, v26
	v_lshlrev_b32_e32 v102, 16, v27
	v_and_b32_e32 v103, 0xffff0000, v27
	s_waitcnt vmcnt(23)
	v_pk_add_f32 v[238:239], v[238:239], v[100:101]
	v_pk_add_f32 v[240:241], v[240:241], v[102:103]
	global_store_dwordx4 v252, v[238:241], s[6:7]
	v_lshlrev_b32_e32 v96, 16, v28
	v_and_b32_e32 v97, 0xffff0000, v28
	v_lshlrev_b32_e32 v98, 16, v29
	v_and_b32_e32 v99, 0xffff0000, v29
	s_waitcnt vmcnt(23)
	v_pk_add_f32 v[242:243], v[242:243], v[96:97]
	v_pk_add_f32 v[244:245], v[244:245], v[98:99]
	v_add_u32_e32 v253, 0x2f000, v254
	global_store_dwordx4 v253, v[242:245], s[6:7] offset:-4096
	v_lshlrev_b32_e32 v100, 16, v30
	v_and_b32_e32 v101, 0xffff0000, v30
	v_lshlrev_b32_e32 v102, 16, v31
	v_and_b32_e32 v103, 0xffff0000, v31
	s_waitcnt vmcnt(23)
	v_pk_add_f32 v[248:249], v[248:249], v[100:101]
	v_pk_add_f32 v[250:251], v[250:251], v[102:103]
	global_store_dwordx4 v253, v[248:251], s[6:7]
	s_barrier
	s_branch .LBB0_1057
